# K/V tiles HBM->LDS directly (global_load_lds_dwordx4 with source-side permutation) in the MLA, MOBA and SLC attention loops; no register staging / ds_write block
# speedup vs baseline: 1.0057x; 1.0057x over previous
; #define LAS __attribute__((address_space(3)))
; __device__ __forceinline__ int v_st(int k, int c) { const int kk = (k & ~0xC) | ((k & 4) << 1) | ((k & 8) >> 1); return ((kk >> 3) * 4 + (c >> 5)) * 512 + ((kk & 7) * 32 + (c & 31)) * 2; }
; __device__ __forceinline__ int v_rd_base(int lane) { return ((lane & 3) << 3) | (((lane >> 2) & 3) << 6) | (((lane >> 4) & 1) << 5) | (((lane >> 5) & 1) << 8); }
; template <int KIND>
; __device__ __forceinline__ void run_unit(LAS char* lds, const UnitArgs& U, int tid_in) {
;     ...
;     const int wid = __builtin_amdgcn_readfirstlane(tid >> 6), lane = tid & 63, r32 = lane & 31, hi = lane >> 5;
;     const int sr = tid >> 4, sc = (tid & 15) * 8;
;     const int qlo = U.P0 + wid * 32, rowpos = qlo + r32;
;     const float sc_ = MLA ? SC192 : SC128; const float C2 = 1.4426950408889634f * sc_;
;     LAS float* wsf = (LAS float*)(lds + OFF_WS) + wid * 96; LAS float* li_l = wsf; LAS float* al_l = wsf + 32; LAS float* g_l = wsf + 64;
;     half8 qr[MLA ? 12 : 8];
;     { const h16* qp = U.Q + (size_t)(wid * 32 + r32) * U.qld + hi * 8;
; #pragma unroll
;       for (int d0 = 0; d0 < (MLA ? 12 : 8); ++d0) qr[d0] = *(const half8*)(qp + d0 * 16); }
;     unsigned mb0 = 0, mb1 = 0, mb2 = 0, mb3 = 0;
;     if constexpr (KIND == K_MOBA) { const int* s = (const int*)U.mk + (size_t)rowpos * 16;
; #pragma unroll
;         for (int i = 0; i < 3; ++i) { const int b = s[i]; if (b >= 0) mb0 |= 1u << b; } }
;     if constexpr (KIND == K_SLC) { const u32x4 m = *(const u32x4*)((const unsigned*)U.mk + (size_t)rowpos * 4); mb0 = m[0]; mb1 = m[1]; mb2 = m[2]; mb3 = m[3]; }
;     const int nvis_row = rowpos >= 31 ? ((rowpos - 31) >> 4) + 1 : 0;
;     const int NT = U.j_hi - U.j_lo;
;     half8 st_k0, st_k1, st_v0, st_v1, st_kr; unsigned dm_lo = 0, dm_hi = 0, dn_lo = 0, dn_hi = 0;
;     const int kws = FA_KSWZ(sr, sc * 2), vst0 = v_st(sr, sc), vst1 = v_st(32 + sr, sc), krw = FA_KRSWZ(tid >> 3, (tid & 7) * 16);
;     const int vb0 = (int)(unsigned)(size_t)(lds + OFF_V) + v_rd_base(lane);
;     ...
;     float m_reg = -1e30f, l_reg = 0.f; f32x16 o[4];
; #pragma unroll
;     for (int d = 0; d < 4; ++d)
; #pragma unroll
;         for (int r = 0; r < 16; ++r) o[d][r] = 0.f;
;     FA_LOADT(U.j_lo); asm volatile("s_waitcnt vmcnt(0)" ::: "memory"); FA_WRITET(0); dm_lo = dn_lo; dm_hi = dn_hi;
.LBB0_4945:
	s_and_b64 vcc, exec, s[0:1]
	s_cbranch_vccz .LBB0_4967
	s_lshl_b32 s8, s14, 21
	v_readlane_b32 s0, v253, 38
	s_add_u32 s6, s0, s8
	v_readlane_b32 s0, v253, 39
	s_addc_u32 s7, s0, 0
	s_lshl_b64 s[0:1], s[2:3], 8
	s_add_u32 s0, s6, s0
	s_addc_u32 s1, s7, s1
	v_readlane_b32 s6, v253, 13
	s_add_u32 s6, s6, s8
	v_readlane_b32 s7, v253, 14
	s_addc_u32 s7, s7, 0
	v_readlane_b32 s9, v252, 4
	s_add_u32 s8, s9, s8
	v_readlane_b32 s9, v252, 5
	s_addc_u32 s9, s9, 0
	s_lshl_b32 s11, s14, 4
	v_readlane_b32 s16, v253, 36
	v_mov_b32_e32 v1, v0
	v_readlane_b32 s17, v253, 37
	s_add_u32 s22, s16, s11
	s_addc_u32 s23, s17, 0
	v_readfirstlane_b32 s11, v1
	s_ashr_i32 s11, s11, 6
	s_lshl_b32 s16, s11, 5
	v_and_b32_e32 v220, 31, v1
	s_add_i32 s17, s16, s2
	v_ashrrev_i32_e32 v204, 4, v1
	v_lshlrev_b32_e32 v7, 3, v1
	v_or_b32_e32 v4, s17, v220
	v_ashrrev_i32_e32 v205, 31, v204
	v_ashrrev_i32_e32 v5, 31, v4
	v_and_b32_e32 v2, 0x78, v7
	v_lshlrev_b64 v[12:13], 8, v[204:205]
	v_lshlrev_b64 v[4:5], 6, v[4:5]
	v_lshlrev_b32_e32 v8, 1, v2
	v_add_u32_e32 v10, 32, v204
	v_lshl_add_u64 v[14:15], s[6:7], 0, v[12:13]
	v_mov_b32_e32 v9, v3
	v_lshl_add_u64 v[4:5], s[22:23], 0, v[4:5]
	v_lshl_add_u64 v[14:15], v[14:15], 0, v[8:9]
	v_ashrrev_i32_e32 v11, 31, v10
	global_load_dwordx3 v[4:6], v[4:5], off
	v_lshl_add_u64 v[12:13], s[8:9], 0, v[12:13]
	global_load_dwordx4 v[146:149], v[14:15], off
	v_lshlrev_b64 v[14:15], 8, v[10:11]
	v_lshl_add_u64 v[16:17], s[6:7], 0, v[14:15]
	v_lshl_add_u64 v[16:17], v[16:17], 0, v[8:9]
	v_lshl_add_u64 v[12:13], v[12:13], 0, v[8:9]
	global_load_dwordx4 v[150:153], v[16:17], off
	global_load_dwordx4 v[154:157], v[12:13], off
	v_lshl_add_u64 v[12:13], s[8:9], 0, v[14:15]
	v_lshl_add_u64 v[12:13], v[12:13], 0, v[8:9]
	global_load_dwordx4 v[158:161], v[12:13], off
	v_and_b32_e32 v11, 0xfffff0, v204
	v_lshlrev_b32_e32 v12, 1, v204
	v_lshrrev_b32_e32 v13, 1, v204
	v_and_b32_e32 v15, 3, v204
	v_and_or_b32 v11, v12, 8, v11
	v_and_or_b32 v12, v13, 4, v15
	v_and_b32_e32 v13, 0xfffff0, v10
	v_lshlrev_b32_e32 v15, 1, v10
	v_or_b32_e32 v10, s16, v220
	v_lshrrev_b32_e32 v18, 1, v11
	v_ashrrev_i32_e32 v11, 31, v10
	v_bfe_u32 v205, v1, 5, 1
	v_lshlrev_b64 v[10:11], 8, v[10:11]
	v_lshlrev_b32_e32 v2, 4, v205
	v_lshl_add_u64 v[10:11], s[0:1], 0, v[10:11]
	v_lshl_add_u64 v[10:11], v[10:11], 0, v[2:3]
	global_load_dwordx4 v[162:165], v[10:11], off
	global_load_dwordx4 v[166:169], v[10:11], off offset:32
	global_load_dwordx4 v[170:173], v[10:11], off offset:64
	global_load_dwordx4 v[174:177], v[10:11], off offset:96
	global_load_dwordx4 v[178:181], v[10:11], off offset:128
	global_load_dwordx4 v[182:185], v[10:11], off offset:160
	global_load_dwordx4 v[186:189], v[10:11], off offset:192
	global_load_dwordx4 v[190:193], v[10:11], off offset:224
	v_and_or_b32 v10, v15, 8, v13
	v_bfe_u32 v14, v7, 5, 2
	v_lshrrev_b32_e32 v10, 1, v10
	v_or_b32_e32 v10, v10, v14
	v_lshlrev_b32_e32 v12, 6, v12
	v_and_b32_e32 v11, 48, v8
	v_or_b32_e32 v13, v18, v14
	v_lshlrev_b32_e32 v10, 9, v10
	v_lshlrev_b32_e32 v13, 9, v13
	v_or3_b32 v225, v10, v12, v11
	v_or3_b32 v224, v13, v12, v11
	v_lshlrev_b32_e32 v16, 8, v204
	v_bitop3_b32 v17, v8, v1, s50 bitop3:0x78
	v_add3_u32 v228, 0, v17, v16
	s_mul_i32 s0, s11, 0x180
	s_waitcnt vmcnt(0)
; __device__ __forceinline__ int v_st(int k, int c) { const int kk = (k & ~0xC) | ((k & 4) << 1) | ((k & 8) >> 1); return ((kk >> 3) * 4 + (c >> 5)) * 512 + ((kk & 7) * 32 + (c & 31)) * 2; }
; __device__ __forceinline__ int v_rd_base(int lane) { return ((lane & 3) << 3) | (((lane >> 2) & 3) << 6) | (((lane >> 4) & 1) << 5) | (((lane >> 5) & 1) << 8); }
; #define FA_WRITET(bf) do { *(LAS half8*)(lds + OFF_K + (bf) * SHM_K + kws) = st_k0; *(LAS half8*)(lds + OFF_K + (bf) * SHM_K + kws + 32 * 256) = st_k1; \
;         *(LAS half8*)(lds + OFF_V + (bf) * SHM_V + vst0) = st_v0; *(LAS half8*)(lds + OFF_V + (bf) * SHM_V + vst1) = st_v1; \
;         if constexpr (MLA) *(LAS half8*)(lds + OFF_KR + (bf) * SHM_KR + krw) = st_kr; } while (0)
; template <int KIND>
; __device__ __forceinline__ void run_unit(LAS char* lds, const UnitArgs& U, int tid_in) {
;     ...
;     if constexpr (KIND == K_MOBA) { const int* s = (const int*)U.mk + (size_t)rowpos * 16;
; #pragma unroll
;         for (int i = 0; i < 3; ++i) { const int b = s[i]; if (b >= 0) mb0 |= 1u << b; } }
;     if constexpr (KIND == K_SLC) { const u32x4 m = *(const u32x4*)((const unsigned*)U.mk + (size_t)rowpos * 4); mb0 = m[0]; mb1 = m[1]; mb2 = m[2]; mb3 = m[3]; }
;     const int nvis_row = rowpos >= 31 ? ((rowpos - 31) >> 4) + 1 : 0;
;     const int NT = U.j_hi - U.j_lo;
;     half8 st_k0, st_k1, st_v0, st_v1, st_kr; unsigned dm_lo = 0, dm_hi = 0, dn_lo = 0, dn_hi = 0;
;     const int kws = FA_KSWZ(sr, sc * 2), vst0 = v_st(sr, sc), vst1 = v_st(32 + sr, sc), krw = FA_KRSWZ(tid >> 3, (tid & 7) * 16);
;     const int vb0 = (int)(unsigned)(size_t)(lds + OFF_V) + v_rd_base(lane);
;     ...
;     float m_reg = -1e30f, l_reg = 0.f; f32x16 o[4];
; #pragma unroll
;     for (int d = 0; d < 4; ++d)
; #pragma unroll
;         for (int r = 0; r < 16; ++r) o[d][r] = 0.f;
;     FA_LOADT(U.j_lo); asm volatile("s_waitcnt vmcnt(0)" ::: "memory"); FA_WRITET(0); dm_lo = dn_lo; dm_hi = dn_hi;
	s_add_i32 s0, s0, 0
	v_lshlrev_b32_e32 v223, 4, v1
	v_and_b32_e32 v221, 63, v1
	s_add_i32 s25, s0, 0x14000
	v_lshl_add_u64 v[206:207], s[6:7], 0, v[8:9]
	s_movk_i32 s6, 0x118
	v_bitop3_b32 v230, v2, v223, s50 bitop3:0x78
	v_lshlrev_b32_e32 v222, 2, v205
	v_mov_b32_e32 v16, v3
	v_mov_b32_e32 v17, v3
	v_lshl_add_u64 v[208:209], s[8:9], 0, v[8:9]
	v_and_b32_e32 v114, 15, v0
	v_bfe_u32 v115, v0, 4, 3
	v_xor_b32_e32 v116, v114, v115
	v_sub_u32_e32 v116, v116, v114
	v_lshlrev_b32_e32 v116, 4, v116
	v_ashrrev_i32_e32 v117, 31, v116
	v_lshl_add_u64 v[206:207], v[206:207], 0, v[116:117]
	v_lshrrev_b32_e32 v118, 7, v0
	v_bfe_u32 v119, v0, 2, 3
	v_lshl_or_b32 v118, v118, 3, v119
	v_and_b32_e32 v120, 4, v118
	v_lshlrev_b32_e32 v120, 1, v120
	v_and_b32_e32 v121, 8, v118
	v_lshrrev_b32_e32 v121, 1, v121
	v_and_b32_e32 v118, 0x33, v118
	v_or3_b32 v118, v118, v120, v121
	v_lshrrev_b32_e32 v119, 4, v0
	v_sub_u32_e32 v118, v118, v119
	v_lshlrev_b32_e32 v118, 8, v118
	v_bfe_u32 v119, v0, 5, 2
	v_lshlrev_b32_e32 v119, 6, v119
	v_and_b32_e32 v120, 3, v0
	v_lshl_or_b32 v119, v120, 4, v119
	v_lshlrev_b32_e32 v120, 4, v114
	v_sub_u32_e32 v119, v119, v120
	v_add_u32_e32 v118, v118, v119
	v_ashrrev_i32_e32 v119, 31, v118
	v_lshl_add_u64 v[208:209], v[208:209], 0, v[118:119]
	v_mov_b32_e32 v8, v3
	s_waitcnt vmcnt(11)
	ds_write_b128 v228, v[146:149] offset:32768
	s_waitcnt vmcnt(10)
	ds_write_b128 v228, v[150:153] offset:40960
	v_lshlrev_b32_e64 v10, v5, 1
	v_cmp_lt_i32_e32 vcc, -1, v5
	v_lshlrev_b32_e64 v11, v6, 1
	v_lshlrev_b32_e64 v12, v4, 1
	v_cndmask_b32_e32 v5, 0, v10, vcc
	v_cmp_lt_i32_e32 vcc, -1, v6
	v_mov_b32_e32 v10, v3
	v_mov_b32_e32 v13, v3
	v_cndmask_b32_e32 v6, 0, v11, vcc
	v_cmp_lt_i32_e32 vcc, -1, v4
	v_mov_b32_e32 v11, v3
	v_mov_b32_e32 v14, v3
	v_cndmask_b32_e32 v4, 0, v12, vcc
	v_or3_b32 v227, v5, v4, v6
	v_add_u32_e32 v4, 0, v224
	s_waitcnt vmcnt(9)
	ds_write_b128 v4, v[154:157]
	v_add_u32_e32 v4, 0, v225
	s_waitcnt vmcnt(8)
	ds_write_b128 v4, v[158:161]
	v_lshlrev_b32_e32 v4, 1, v1
	v_and_b32_e32 v4, 32, v4
	v_and_b32_e32 v1, 0x70, v223
	v_and_b32_e32 v5, 0xc0, v223
	v_bitop3_b32 v231, v2, v1, 32 bitop3:0x36
	v_bitop3_b32 v232, v2, v1, 64 bitop3:0x36
	v_bitop3_b32 v233, v2, v1, s77 bitop3:0x36
	v_add_u32_e32 v1, s25, v2
	v_and_or_b32 v2, v7, s6, v4
	s_add_i32 s6, s16, 0x1ec5
	v_add3_u32 v234, v5, 0, v2
	v_add_u32_e32 v2, s6, v220
	v_sub_u32_e32 v2, v2, v222
	v_subrev_u32_e32 v235, s12, v2
	v_mov_b32_e32 v2, v3
	v_mov_b32_e32 v4, v3
	v_mov_b32_e32 v5, v3
	v_mov_b32_e32 v6, v3
	v_mov_b32_e32 v7, v3
	v_mov_b32_e32 v12, v3
	v_mov_b32_e32 v15, v3
	v_mov_b64_e32 v[32:33], v[16:17]
	v_mov_b64_e32 v[48:49], v[16:17]
	v_mov_b64_e32 v[64:65], v[16:17]
	v_mov_b64_e32 v[80:81], v[16:17]
	s_mov_b32 s22, 63
	s_mov_b32 s23, 0
	s_or_b32 s24, s17, 31
	v_lshl_add_u32 v229, v220, 8, 0
	v_cmp_gt_u32_e64 s[0:1], 32, v221
	v_lshl_add_u32 v226, v220, 2, s25
	s_ashr_i32 s25, s2, 8
	v_mov_b32_e32 v237, 0
	v_mov_b32_e32 v236, 0xf149f2ca
	s_movk_i32 s37, 0x4000
	v_mov_b64_e32 v[30:31], v[14:15]
	v_mov_b64_e32 v[28:29], v[12:13]
	v_mov_b64_e32 v[26:27], v[10:11]
	v_mov_b64_e32 v[24:25], v[8:9]
	v_mov_b64_e32 v[22:23], v[6:7]
	v_mov_b64_e32 v[20:21], v[4:5]
	v_mov_b64_e32 v[18:19], v[2:3]
	v_mov_b64_e32 v[46:47], v[14:15]
	v_mov_b64_e32 v[44:45], v[12:13]
	v_mov_b64_e32 v[42:43], v[10:11]
	v_mov_b64_e32 v[40:41], v[8:9]
	v_mov_b64_e32 v[38:39], v[6:7]
	v_mov_b64_e32 v[36:37], v[4:5]
	v_mov_b64_e32 v[34:35], v[2:3]
	v_mov_b64_e32 v[62:63], v[14:15]
	v_mov_b64_e32 v[60:61], v[12:13]
	v_mov_b64_e32 v[58:59], v[10:11]
	v_mov_b64_e32 v[56:57], v[8:9]
	v_mov_b64_e32 v[54:55], v[6:7]
	v_mov_b64_e32 v[52:53], v[4:5]
	v_mov_b64_e32 v[50:51], v[2:3]
	v_mov_b64_e32 v[78:79], v[14:15]
	v_mov_b64_e32 v[76:77], v[12:13]
	v_mov_b64_e32 v[74:75], v[10:11]
	v_mov_b64_e32 v[72:73], v[8:9]
	v_mov_b64_e32 v[70:71], v[6:7]
	v_mov_b64_e32 v[68:69], v[4:5]
	v_mov_b64_e32 v[66:67], v[2:3]
	s_waitcnt lgkmcnt(0)
	s_barrier
	s_branch .LBB0_4948

; template <int KIND>
; __device__ __forceinline__ void run_unit(LAS char* lds, const UnitArgs& U, int tid_in) {
;     ...
;         if (t + 1 < NT) FA_LOADT(U.j_lo + t + 1);
.LBB0_4950:
	s_sub_i32 s8, s22, 63
	s_and_b32 s9, s23, 1
	v_mov_b32_e32 v2, s9
	s_cmp_gt_i32 s8, s24
	s_cbranch_scc1 .Lmoba_skipq
	v_lshlrev_b32_e32 v2, 14, v2
	v_add_u32_e32 v4, v229, v2
	v_add_u32_e32 v16, v4, v230
	v_add_u32_e32 v17, v4, v231
	v_add_u32_e32 v102, v4, v232
	v_add_u32_e32 v103, v4, v233
	ds_read_b128 v[4:7], v16 offset:32768
	ds_read_b128 v[8:11], v16 offset:40960
	ds_read_b128 v[12:15], v17 offset:32768
	ds_read_b128 v[82:85], v17 offset:40960
	ds_read_b128 v[86:89], v102 offset:32768
	ds_read_b128 v[90:93], v102 offset:40960
	ds_read_b128 v[94:97], v103 offset:32768
	ds_read_b128 v[98:101], v103 offset:40960
	s_and_b64 vcc, exec, s[6:7]
	s_cbranch_vccz .Lmoba_q_nold
	v_readfirstlane_b32 vcc_hi, v0
	s_and_b32 vcc_lo, s37, 0x4000
	s_lshr_b32 vcc_hi, vcc_hi, 6
	s_lshl_b32 vcc_hi, vcc_hi, 10
	s_add_i32 vcc_lo, vcc_lo, vcc_hi
	v_add_u32_e32 v114, s22, v204
	v_add_u32_e32 v116, 1, v114
	v_ashrrev_i32_e32 v117, 31, v116
	v_add_u32_e32 v120, 33, v114
	v_lshlrev_b64 v[116:117], 8, v[116:117]
	v_ashrrev_i32_e32 v121, 31, v120
	s_add_i32 m0, vcc_lo, 0x8000
	v_lshl_add_u64 v[118:119], v[206:207], 0, v[116:117]
	v_lshlrev_b64 v[120:121], 8, v[120:121]
	global_load_lds_dwordx4 v[118:119], off
	s_add_i32 m0, vcc_lo, 0xa000
	v_lshl_add_u64 v[122:123], v[206:207], 0, v[120:121]
	v_lshl_add_u64 v[116:117], v[208:209], 0, v[116:117]
	global_load_lds_dwordx4 v[122:123], off
	s_mov_b32 m0, vcc_lo
	v_lshl_add_u64 v[118:119], v[208:209], 0, v[120:121]
	s_nop 0
	global_load_lds_dwordx4 v[116:117], off
	s_add_i32 m0, vcc_lo, 0x2000
	s_nop 0
	global_load_lds_dwordx4 v[118:119], off

; #define FA_SBAR() __builtin_amdgcn_sched_barrier(0)
; #define FA_WRITET(bf) do { *(LAS half8*)(lds + OFF_K + (bf) * SHM_K + kws) = st_k0; *(LAS half8*)(lds + OFF_K + (bf) * SHM_K + kws + 32 * 256) = st_k1; \
;         *(LAS half8*)(lds + OFF_V + (bf) * SHM_V + vst0) = st_v0; *(LAS half8*)(lds + OFF_V + (bf) * SHM_V + vst1) = st_v1; \
;         if constexpr (MLA) *(LAS half8*)(lds + OFF_KR + (bf) * SHM_KR + krw) = st_kr; } while (0)
; template <int KIND>
; __device__ __forceinline__ void run_unit(LAS char* lds, const UnitArgs& U, int tid_in) {
;     ...
;     for (int t = 0; t < NT; ++t) {
;         if (t + 1 < NT) FA_LOADT(U.j_lo + t + 1);
;         FA_SBAR();
;         FA_STEP(t);
;         FA_SBAR();
;         if (t + 1 < NT) { asm volatile("s_waitcnt vmcnt(0)" ::: "memory"); FA_WRITET((t + 1) & 1); dm_lo = dn_lo; dm_hi = dn_hi; }
;         __syncthreads();
.LBB0_4962:
	s_waitcnt vmcnt(0)
	s_branch .LBB0_4947
.Lmoba_skipq:
	s_and_b64 vcc, exec, s[6:7]
	s_cbranch_vccz .LBB0_4962
	v_readfirstlane_b32 vcc_hi, v0
	s_and_b32 vcc_lo, s37, 0x4000
	s_lshr_b32 vcc_hi, vcc_hi, 6
	s_lshl_b32 vcc_hi, vcc_hi, 10
	s_add_i32 vcc_lo, vcc_lo, vcc_hi
	v_add_u32_e32 v2, s22, v204
	v_add_u32_e32 v4, 1, v2
	v_ashrrev_i32_e32 v5, 31, v4
	v_add_u32_e32 v8, 33, v2
	v_lshlrev_b64 v[4:5], 8, v[4:5]
	v_ashrrev_i32_e32 v9, 31, v8
	s_add_i32 m0, vcc_lo, 0x8000
	v_lshl_add_u64 v[6:7], v[206:207], 0, v[4:5]
	v_lshlrev_b64 v[8:9], 8, v[8:9]
	global_load_lds_dwordx4 v[6:7], off
	s_add_i32 m0, vcc_lo, 0xa000
	v_lshl_add_u64 v[10:11], v[206:207], 0, v[8:9]
	v_lshl_add_u64 v[4:5], v[208:209], 0, v[4:5]
	global_load_lds_dwordx4 v[10:11], off
	s_mov_b32 m0, vcc_lo
	v_lshl_add_u64 v[6:7], v[208:209], 0, v[8:9]
	s_nop 0
	global_load_lds_dwordx4 v[4:5], off
	s_add_i32 m0, vcc_lo, 0x2000
	s_nop 0
	global_load_lds_dwordx4 v[6:7], off
	s_branch .LBB0_4962

; #define LAS __attribute__((address_space(3)))
; __device__ __forceinline__ int v_st(int k, int c) { const int kk = (k & ~0xC) | ((k & 4) << 1) | ((k & 8) >> 1); return ((kk >> 3) * 4 + (c >> 5)) * 512 + ((kk & 7) * 32 + (c & 31)) * 2; }
; __device__ __forceinline__ int v_rd_base(int lane) { return ((lane & 3) << 3) | (((lane >> 2) & 3) << 6) | (((lane >> 4) & 1) << 5) | (((lane >> 5) & 1) << 8); }
; template <int KIND>
; __device__ __forceinline__ void run_unit(LAS char* lds, const UnitArgs& U, int tid_in) {
;     ...
;     const int wid = __builtin_amdgcn_readfirstlane(tid >> 6), lane = tid & 63, r32 = lane & 31, hi = lane >> 5;
;     const int sr = tid >> 4, sc = (tid & 15) * 8;
;     const int qlo = U.P0 + wid * 32, rowpos = qlo + r32;
;     const float sc_ = MLA ? SC192 : SC128; const float C2 = 1.4426950408889634f * sc_;
;     LAS float* wsf = (LAS float*)(lds + OFF_WS) + wid * 96; LAS float* li_l = wsf; LAS float* al_l = wsf + 32; LAS float* g_l = wsf + 64;
;     half8 qr[MLA ? 12 : 8];
;     { const h16* qp = U.Q + (size_t)(wid * 32 + r32) * U.qld + hi * 8;
; #pragma unroll
;       for (int d0 = 0; d0 < (MLA ? 12 : 8); ++d0) qr[d0] = *(const half8*)(qp + d0 * 16); }
;     unsigned mb0 = 0, mb1 = 0, mb2 = 0, mb3 = 0;
;     if constexpr (KIND == K_MOBA) { const int* s = (const int*)U.mk + (size_t)rowpos * 16;
; #pragma unroll
;         for (int i = 0; i < 3; ++i) { const int b = s[i]; if (b >= 0) mb0 |= 1u << b; } }
;     if constexpr (KIND == K_SLC) { const u32x4 m = *(const u32x4*)((const unsigned*)U.mk + (size_t)rowpos * 4); mb0 = m[0]; mb1 = m[1]; mb2 = m[2]; mb3 = m[3]; }
;     const int nvis_row = rowpos >= 31 ? ((rowpos - 31) >> 4) + 1 : 0;
;     const int NT = U.j_hi - U.j_lo;
;     half8 st_k0, st_k1, st_v0, st_v1, st_kr; unsigned dm_lo = 0, dm_hi = 0, dn_lo = 0, dn_hi = 0;
;     const int kws = FA_KSWZ(sr, sc * 2), vst0 = v_st(sr, sc), vst1 = v_st(32 + sr, sc), krw = FA_KRSWZ(tid >> 3, (tid & 7) * 16);
;     const int vb0 = (int)(unsigned)(size_t)(lds + OFF_V) + v_rd_base(lane);
;     ...
;     float m_reg = -1e30f, l_reg = 0.f; f32x16 o[4];
; #pragma unroll
;     for (int d = 0; d < 4; ++d)
; #pragma unroll
;         for (int r = 0; r < 16; ++r) o[d][r] = 0.f;
;     FA_LOADT(U.j_lo); asm volatile("s_waitcnt vmcnt(0)" ::: "memory"); FA_WRITET(0); dm_lo = dn_lo; dm_hi = dn_hi;
.LBB0_4987:
	s_and_b64 vcc, exec, s[0:1]
	s_cbranch_vccz .LBB0_4921
	v_mov_b32_e32 v1, v0
	s_lshl_b32 s0, s14, 21
	s_waitcnt vmcnt(10)
	v_ashrrev_i32_e32 v166, 4, v1
	v_readlane_b32 s1, v254, 0
	v_lshlrev_b32_e32 v14, 3, v1
	v_ashrrev_i32_e32 v167, 31, v166
	v_readlane_b32 s40, v254, 2
	s_add_u32 s6, s1, s0
	v_readlane_b32 s0, v254, 1
	v_and_b32_e32 v2, 0x78, v14
	v_lshlrev_b64 v[8:9], 8, v[166:167]
	v_readlane_b32 s41, v254, 3
	s_addc_u32 s7, s0, 0
	s_lshl_b64 s[0:1], s[2:3], 8
	v_lshlrev_b32_e32 v4, 1, v2
	v_add_u32_e32 v6, 32, v166
	v_lshl_add_u64 v[10:11], s[40:41], 0, v[8:9]
	v_mov_b32_e32 v5, v3
	v_readfirstlane_b32 s10, v1
	s_add_u32 s8, s6, s0
	v_lshl_add_u64 v[10:11], v[10:11], 0, v[4:5]
	v_ashrrev_i32_e32 v7, 31, v6
	v_readlane_b32 s38, v251, 50
	s_addc_u32 s9, s7, s1
	s_ashr_i32 s16, s10, 6
	global_load_dwordx4 v[114:117], v[10:11], off
	v_lshlrev_b64 v[10:11], 8, v[6:7]
	v_readlane_b32 s39, v251, 51
	s_lshl_b32 s17, s16, 5
	v_lshl_add_u64 v[12:13], s[40:41], 0, v[10:11]
	v_lshl_add_u64 v[8:9], s[38:39], 0, v[8:9]
	s_waitcnt vmcnt(9)
	v_and_b32_e32 v174, 31, v1
	s_add_i32 s23, s17, s2
	v_lshl_add_u64 v[12:13], v[12:13], 0, v[4:5]
	v_lshl_add_u64 v[8:9], v[8:9], 0, v[4:5]
	v_or_b32_e32 v168, s23, v174
	v_readlane_b32 s0, v253, 58
	global_load_dwordx4 v[118:121], v[12:13], off
	global_load_dwordx4 v[122:125], v[8:9], off
	v_lshl_add_u64 v[8:9], s[38:39], 0, v[10:11]
	v_ashrrev_i32_e32 v169, 31, v168
	v_readlane_b32 s1, v253, 59
	v_lshl_add_u64 v[8:9], v[8:9], 0, v[4:5]
	global_load_dwordx4 v[126:129], v[8:9], off
	v_lshl_add_u64 v[10:11], v[168:169], 4, s[0:1]
	global_load_dwordx4 v[130:133], v[10:11], off
	v_or_b32_e32 v8, s17, v174
	v_ashrrev_i32_e32 v9, 31, v8
	v_bfe_u32 v167, v1, 5, 1
	v_lshlrev_b64 v[8:9], 8, v[8:9]
	v_lshlrev_b32_e32 v2, 4, v167
	v_lshl_add_u64 v[8:9], s[8:9], 0, v[8:9]
	v_lshl_add_u64 v[8:9], v[8:9], 0, v[2:3]
	global_load_dwordx4 v[134:137], v[8:9], off
	global_load_dwordx4 v[138:141], v[8:9], off offset:32
	global_load_dwordx4 v[142:145], v[8:9], off offset:64
	global_load_dwordx4 v[146:149], v[8:9], off offset:96
	global_load_dwordx4 v[150:153], v[8:9], off offset:128
	global_load_dwordx4 v[154:157], v[8:9], off offset:160
	global_load_dwordx4 v[158:161], v[8:9], off offset:192
	global_load_dwordx4 v[162:165], v[8:9], off offset:224
	v_and_b32_e32 v7, 0xfffff0, v166
	v_lshlrev_b32_e32 v12, 1, v166
	v_and_or_b32 v7, v12, 8, v7
	v_and_b32_e32 v11, 0xfffff0, v6
	v_lshlrev_b32_e32 v6, 1, v6
	v_lshrrev_b32_e32 v13, 1, v166
	v_bfe_u32 v8, v14, 5, 2
	v_and_b32_e32 v9, 3, v166
	v_lshrrev_b32_e32 v7, 1, v7
	v_and_or_b32 v6, v6, 8, v11
	v_and_or_b32 v9, v13, 4, v9
	v_or_b32_e32 v7, v7, v8
	v_lshrrev_b32_e32 v6, 1, v6
	v_lshlrev_b32_e32 v9, 6, v9
	v_and_b32_e32 v11, 48, v4
	v_lshlrev_b32_e32 v7, 9, v7
	v_or_b32_e32 v6, v6, v8
	v_lshlrev_b32_e32 v10, 8, v166
	s_mul_i32 s0, s16, 0x180
	v_bitop3_b32 v12, v4, v1, s50 bitop3:0x78
	v_lshlrev_b32_e32 v6, 9, v6
	v_or3_b32 v180, v7, v9, v11
	s_add_i32 s0, s0, 0
	v_add3_u32 v179, 0, v12, v10
	v_or3_b32 v181, v6, v9, v11
	v_add_u32_e32 v6, 0, v180
	v_lshlrev_b32_e32 v177, 4, v1
	v_and_b32_e32 v176, 63, v1
	s_add_i32 s6, s0, 0x14000
	v_add_u32_e32 v7, 0, v181
	s_waitcnt vmcnt(0)
	v_lshl_add_u32 v178, v174, 2, s6
	v_bitop3_b32 v183, v2, v177, s50 bitop3:0x78
	v_lshlrev_b32_e32 v175, 2, v167
	v_mov_b32_e32 v16, v3
	s_waitcnt vmcnt(12)
	ds_write_b128 v179, v[114:117] offset:32768
	s_waitcnt vmcnt(11)
	ds_write_b128 v179, v[118:121] offset:40960
	s_waitcnt vmcnt(10)
	ds_write_b128 v6, v[122:125]
	s_waitcnt vmcnt(9)
	ds_write_b128 v7, v[126:129]
	v_lshlrev_b32_e32 v6, 1, v1
	v_and_b32_e32 v1, 0x70, v177
	v_and_b32_e32 v6, 32, v6
	v_bitop3_b32 v184, v2, v1, 32 bitop3:0x36
	v_bitop3_b32 v185, v2, v1, 64 bitop3:0x36
	v_bitop3_b32 v186, v2, v1, s77 bitop3:0x36
	v_add_u32_e32 v1, s6, v2
	s_movk_i32 s6, 0x118
	v_and_b32_e32 v7, 0xc0, v177
	v_and_or_b32 v2, v14, s6, v6
	s_add_i32 s6, s17, 0x1ec5
	v_add3_u32 v187, v7, 0, v2
	v_add_u32_e32 v2, s6, v174
	v_sub_u32_e32 v2, v2, v175
	v_mov_b32_e32 v17, v3
	v_lshl_add_u64 v[170:171], s[40:41], 0, v[4:5]
	v_lshl_add_u64 v[172:173], s[38:39], 0, v[4:5]
	v_and_b32_e32 v98, 15, v0
	v_bfe_u32 v99, v0, 4, 3
	v_xor_b32_e32 v100, v98, v99
	v_sub_u32_e32 v100, v100, v98
	v_lshlrev_b32_e32 v100, 4, v100
	v_ashrrev_i32_e32 v101, 31, v100
	v_lshl_add_u64 v[170:171], v[170:171], 0, v[100:101]
	v_lshrrev_b32_e32 v102, 7, v0
	v_bfe_u32 v103, v0, 2, 3
	v_lshl_or_b32 v102, v102, 3, v103
	v_and_b32_e32 v104, 4, v102
	v_lshlrev_b32_e32 v104, 1, v104
	v_and_b32_e32 v105, 8, v102
	v_lshrrev_b32_e32 v105, 1, v105
	v_and_b32_e32 v102, 0x33, v102
	v_or3_b32 v102, v102, v104, v105
	v_lshrrev_b32_e32 v103, 4, v0
	v_sub_u32_e32 v102, v102, v103
	v_lshlrev_b32_e32 v102, 8, v102
	v_bfe_u32 v103, v0, 5, 2
	v_lshlrev_b32_e32 v103, 6, v103
	v_and_b32_e32 v104, 3, v0
	v_lshl_or_b32 v103, v104, 4, v103
	v_lshlrev_b32_e32 v104, 4, v98
	v_sub_u32_e32 v103, v103, v104
	v_add_u32_e32 v102, v102, v103
	v_ashrrev_i32_e32 v103, 31, v102
	v_lshl_add_u64 v[172:173], v[172:173], 0, v[102:103]
	v_subrev_u32_e32 v188, s12, v2
	v_mov_b32_e32 v2, v3
	v_mov_b32_e32 v4, v3
	v_mov_b32_e32 v6, v3
	v_mov_b32_e32 v7, v3
	v_mov_b32_e32 v8, v3
	v_mov_b32_e32 v9, v3
	v_mov_b32_e32 v10, v3
	v_mov_b32_e32 v11, v3
	v_mov_b32_e32 v12, v3
	v_mov_b32_e32 v13, v3
	v_mov_b32_e32 v14, v3
	v_mov_b32_e32 v15, v3
	v_mov_b64_e32 v[32:33], v[16:17]
	v_mov_b64_e32 v[48:49], v[16:17]
	v_mov_b64_e32 v[64:65], v[16:17]
	v_mov_b64_e32 v[80:81], v[16:17]
	s_mov_b32 s22, 63
	s_or_b32 s24, s23, 31
	v_lshl_add_u32 v182, v174, 8, 0
	v_cmp_gt_u32_e64 s[0:1], 32, v176
	s_mov_b32 s25, 0
	v_mov_b32_e32 v190, 0
	v_mov_b32_e32 v189, 0xf149f2ca
	s_movk_i32 s37, 0x4000
	v_mov_b64_e32 v[30:31], v[14:15]
	v_mov_b64_e32 v[28:29], v[12:13]
	v_mov_b64_e32 v[26:27], v[10:11]
	v_mov_b64_e32 v[24:25], v[8:9]
	v_mov_b64_e32 v[22:23], v[6:7]
	v_mov_b64_e32 v[20:21], v[4:5]
	v_mov_b64_e32 v[18:19], v[2:3]
	v_mov_b64_e32 v[46:47], v[14:15]
	v_mov_b64_e32 v[44:45], v[12:13]
	v_mov_b64_e32 v[42:43], v[10:11]
	v_mov_b64_e32 v[40:41], v[8:9]
	v_mov_b64_e32 v[38:39], v[6:7]
	v_mov_b64_e32 v[36:37], v[4:5]
	v_mov_b64_e32 v[34:35], v[2:3]
	v_mov_b64_e32 v[62:63], v[14:15]
	v_mov_b64_e32 v[60:61], v[12:13]
	v_mov_b64_e32 v[58:59], v[10:11]
	v_mov_b64_e32 v[56:57], v[8:9]
	v_mov_b64_e32 v[54:55], v[6:7]
	v_mov_b64_e32 v[52:53], v[4:5]
	v_mov_b64_e32 v[50:51], v[2:3]
	v_mov_b64_e32 v[78:79], v[14:15]
	v_mov_b64_e32 v[76:77], v[12:13]
	v_mov_b64_e32 v[74:75], v[10:11]
	v_mov_b64_e32 v[72:73], v[8:9]
	v_mov_b64_e32 v[70:71], v[6:7]
	v_mov_b64_e32 v[68:69], v[4:5]
	v_mov_b64_e32 v[66:67], v[2:3]
	s_waitcnt lgkmcnt(0)
	s_barrier
	s_branch .LBB0_4990

; template <int KIND>
; __device__ __forceinline__ void run_unit(LAS char* lds, const UnitArgs& U, int tid_in) {
;     ...
;         if (t + 1 < NT) FA_LOADT(U.j_lo + t + 1);
.LBB0_4992:
	s_sub_i32 s10, s22, 63
	s_and_b32 s11, s25, 1
	v_mov_b32_e32 v2, s11
	s_cmp_gt_i32 s10, s24
	s_cbranch_scc1 .Lslc_skipq
	v_lshlrev_b32_e32 v2, 14, v2
	v_add_u32_e32 v4, v182, v2
	v_add_u32_e32 v16, v4, v183
	v_add_u32_e32 v17, v4, v184
	v_add_u32_e32 v191, v4, v185
	v_add_u32_e32 v196, v4, v186
	ds_read_b128 v[4:7], v16 offset:32768
	ds_read_b128 v[8:11], v16 offset:40960
	ds_read_b128 v[12:15], v17 offset:32768
	ds_read_b128 v[192:195], v17 offset:40960
	ds_read_b128 v[204:207], v191 offset:32768
	ds_read_b128 v[220:223], v191 offset:40960
	ds_read_b128 v[224:227], v196 offset:32768
	ds_read_b128 v[228:231], v196 offset:40960
	s_and_b64 vcc, exec, s[6:7]
	s_cbranch_vccz .Lslc_q_nold
	v_readfirstlane_b32 vcc_hi, v0
	s_and_b32 vcc_lo, s37, 0x4000
	s_lshr_b32 vcc_hi, vcc_hi, 6
	s_lshl_b32 vcc_hi, vcc_hi, 10
	s_add_i32 vcc_lo, vcc_lo, vcc_hi
	v_add_u32_e32 v98, s22, v166
	v_add_u32_e32 v100, 1, v98
	v_ashrrev_i32_e32 v101, 31, v100
	v_add_u32_e32 v104, 33, v98
	v_lshlrev_b64 v[100:101], 8, v[100:101]
	v_ashrrev_i32_e32 v105, 31, v104
	s_add_i32 m0, vcc_lo, 0x8000
	v_lshl_add_u64 v[102:103], v[170:171], 0, v[100:101]
	v_lshlrev_b64 v[104:105], 8, v[104:105]
	global_load_lds_dwordx4 v[102:103], off
	s_add_i32 m0, vcc_lo, 0xa000
	v_lshl_add_u64 v[106:107], v[170:171], 0, v[104:105]
	v_lshl_add_u64 v[100:101], v[172:173], 0, v[100:101]
	global_load_lds_dwordx4 v[106:107], off
	s_mov_b32 m0, vcc_lo
	v_lshl_add_u64 v[102:103], v[172:173], 0, v[104:105]
	s_nop 0
	global_load_lds_dwordx4 v[100:101], off
	s_add_i32 m0, vcc_lo, 0x2000
	s_nop 0
	global_load_lds_dwordx4 v[102:103], off

; template <int KIND>
; __device__ __forceinline__ void run_unit(LAS char* lds, const UnitArgs& U, int tid_in) {
;     ...
;         if (t + 1 < NT) FA_LOADT(U.j_lo + t + 1);
.Lslc_skipq:
	s_and_b64 vcc, exec, s[6:7]
	s_cbranch_vccz .LBB0_5000
	v_readfirstlane_b32 vcc_hi, v0
	s_and_b32 vcc_lo, s37, 0x4000
	s_lshr_b32 vcc_hi, vcc_hi, 6
	s_lshl_b32 vcc_hi, vcc_hi, 10
	s_add_i32 vcc_lo, vcc_lo, vcc_hi
	v_add_u32_e32 v2, s22, v166
	v_add_u32_e32 v4, 1, v2
	v_ashrrev_i32_e32 v5, 31, v4
	v_add_u32_e32 v8, 33, v2
	v_lshlrev_b64 v[4:5], 8, v[4:5]
	v_ashrrev_i32_e32 v9, 31, v8
	s_add_i32 m0, vcc_lo, 0x8000
	v_lshl_add_u64 v[6:7], v[170:171], 0, v[4:5]
	v_lshlrev_b64 v[8:9], 8, v[8:9]
	global_load_lds_dwordx4 v[6:7], off
	s_add_i32 m0, vcc_lo, 0xa000
	v_lshl_add_u64 v[10:11], v[170:171], 0, v[8:9]
	v_lshl_add_u64 v[4:5], v[172:173], 0, v[4:5]
	global_load_lds_dwordx4 v[10:11], off
	s_mov_b32 m0, vcc_lo
	v_lshl_add_u64 v[6:7], v[172:173], 0, v[8:9]
	s_nop 0
	global_load_lds_dwordx4 v[4:5], off
	s_add_i32 m0, vcc_lo, 0x2000
	s_nop 0
	global_load_lds_dwordx4 v[6:7], off
	s_branch .LBB0_5000
